# mergeA: per-iteration loads issued together (one round trip per grid-stride iteration); PEER value pass sum-of-squares via permlane/DPP
# speedup vs baseline: 1.0350x; 1.0062x over previous
; __device__ __forceinline__ unsigned pack2(float lo, float hi) { unsigned r; asm("v_cvt_pk_bf16_f32 %0, %1, %2" : "=v"(r) : "v"(lo), "v"(hi)); return r; }
; __device__ __forceinline__ float bflo(unsigned u) { return __uint_as_float(u << 16); }
; __device__ __forceinline__ float bfhi(unsigned u) { return __uint_as_float(u & 0xffff0000u); }
; __device__ void phase_mergeA(const Params& p, int l) {
;     ...
;   for (int i = blockIdx.x * NTHREADS + tid; i < total; i += gridDim.x * NTHREADS) {
;     const int tok = i / 48, rem = i % 48, h = rem >> 3, c = rem & 7;
;     const float l0 = p.lseA[(size_t)tok * 6 + h], l1 = p.lseA[((size_t)T_TOK + tok) * 6 + h], l2 = p.lseA[((size_t)2 * T_TOK + tok) * 6 + h];
;     const float mx = fmaxf(l0, fmaxf(l1, l2));
;     float w0 = __expf(l0 - mx), w1 = __expf(l1 - mx), w2 = __expf(l2 - mx);
;     const float inv = 1.f / (w0 + w1 + w2);
;     w0 *= inv; w1 *= inv; w2 *= inv;
;     const size_t off = (size_t)tok * 384 + h * 64 + c * 8;
;     const u32x4 a0 = *(const u32x4*)(p.oA + off), a1 = *(const u32x4*)(p.oA + (size_t)T_TOK * 384 + off), a2 = *(const u32x4*)(p.oA + (size_t)2 * T_TOK * 384 + off);
;     u32x4 o;
; #pragma unroll
;     for (int e = 0; e < 4; ++e) {
;       const float lo = w0 * bflo(a0[e]) + w1 * bflo(a1[e]) + w2 * bflo(a2[e]);
;       const float hi = w0 * bfhi(a0[e]) + w1 * bfhi(a1[e]) + w2 * bfhi(a2[e]);
;       o[e] = pack2(lo, hi);
;     }
;     *(u32x4*)(p.y + (size_t)tok * 1280 + h * 64 + c * 8) = o;
;   }
.LBB0_785:
	v_mul_hi_i32 v0, v6, s11
	v_lshrrev_b32_e32 v2, 31, v0
	v_ashrrev_i32_e32 v0, 3, v0
	v_add_u32_e32 v0, v0, v2
	s_movk_i32 s4, 0xffd0
	v_mad_u64_u32 v[2:3], s[4:5], v0, s4, v[6:7]
	v_ashrrev_i32_e32 v2, 3, v2
	v_ashrrev_i32_e32 v3, 31, v2
	v_mad_i64_i32 v[4:5], s[4:5], v0, 24, s[90:91]
	v_lshl_add_u64 v[4:5], v[2:3], 2, v[4:5]
	s_mov_b32 s4, 0x60000
	v_add_co_u32_e32 v8, vcc, s4, v4
	global_load_dword v3, v[4:5], off
	s_nop 0
	v_addc_co_u32_e32 v9, vcc, 0, v5, vcc
	global_load_dword v8, v[8:9], off
	v_add_co_u32_e32 v4, vcc, s13, v4
	v_and_b32_e32 v24, 56, v7
	s_nop 0
	v_addc_co_u32_e32 v5, vcc, 0, v5, vcc
	global_load_dword v4, v[4:5], off
	v_lshlrev_b32_e32 v46, 6, v2
	v_ashrrev_i32_e32 v47, 31, v46
	s_movk_i32 s4, 0x180
	v_mad_i64_i32 v[48:49], s[4:5], v0, s4, v[46:47]
	v_or_b32_e32 v48, v48, v24
	v_lshlrev_b64 v[48:49], 1, v[48:49]
	v_lshl_add_u64 v[50:51], s[86:87], 0, v[48:49]
	global_load_dwordx4 v[34:37], v[50:51], off
	v_lshl_add_u64 v[50:51], s[6:7], 0, v[48:49]
	global_load_dwordx4 v[38:41], v[50:51], off
	v_lshl_add_u64 v[50:51], s[8:9], 0, v[48:49]
	global_load_dwordx4 v[42:45], v[50:51], off
	v_add_u32_e32 v6, s72, v6
	v_add_u32_e32 v7, s10, v7
	s_waitcnt vmcnt(0)
	v_max3_f32 v5, v3, v8, v4
	v_sub_f32_e32 v3, v3, v5
	v_mul_f32_e32 v3, 0x3fb8aa3b, v3
	v_exp_f32_e32 v11, v3
	v_sub_f32_e32 v3, v8, v5
	v_mul_f32_e32 v3, 0x3fb8aa3b, v3
	v_sub_f32_e32 v4, v4, v5
	v_exp_f32_e32 v3, v3
	v_mul_f32_e32 v4, 0x3fb8aa3b, v4
	v_exp_f32_e32 v10, v4
	v_add_f32_e32 v4, v11, v3
	v_add_f32_e32 v4, v10, v4
	v_div_scale_f32 v5, s[4:5], v4, v4, 1.0
	v_rcp_f32_e32 v8, v5
	s_movk_i32 s4, 0x180
	v_fma_f32 v9, -v5, v8, 1.0
	v_fmac_f32_e32 v8, v9, v8
	v_div_scale_f32 v9, vcc, 1.0, v4, 1.0
	v_mul_f32_e32 v14, v9, v8
	v_fma_f32 v15, -v5, v14, v9
	v_fmac_f32_e32 v14, v15, v8
	v_fma_f32 v5, -v5, v14, v9
	v_div_fmas_f32 v5, v5, v8, v14
	v_lshlrev_b32_e32 v8, 6, v2
	v_div_fixup_f32 v22, v5, v4, 1.0
	v_ashrrev_i32_e32 v9, 31, v8
	v_mul_f32_e32 v23, v3, v22
	v_mad_i64_i32 v[2:3], s[4:5], v0, s4, v[8:9]
	v_or_b32_e32 v2, v2, v24
	v_lshlrev_b64 v[18:19], 1, v[2:3]
	v_lshl_add_u64 v[2:3], s[86:87], 0, v[18:19]
	v_lshl_add_u64 v[14:15], s[6:7], 0, v[18:19]
	v_lshl_add_u64 v[18:19], s[8:9], 0, v[18:19]
	v_mov_b32_e32 v2, v34
	v_mov_b32_e32 v3, v35
	v_mov_b32_e32 v4, v36
	v_mov_b32_e32 v5, v37
	v_pk_mul_f32 v[10:11], v[10:11], v[22:23] op_sel_hi:[1,0]
	v_mov_b32_e32 v14, v38
	v_mov_b32_e32 v15, v39
	v_mov_b32_e32 v16, v40
	v_mov_b32_e32 v17, v41
	s_waitcnt vmcnt(0)
	v_lshlrev_b32_e32 v25, 16, v14
	v_mov_b32_e32 v18, v42
	v_mov_b32_e32 v19, v43
	v_mov_b32_e32 v20, v44
	v_mov_b32_e32 v21, v45
	v_and_b32_e32 v26, 0xffff0000, v14
	v_lshlrev_b32_e32 v27, 16, v15
	v_and_b32_e32 v28, 0xffff0000, v15
	v_lshlrev_b32_e32 v15, 16, v2
	v_lshlrev_b32_e32 v29, 16, v16
	v_and_b32_e32 v16, 0xffff0000, v16
	v_lshlrev_b32_e32 v30, 16, v17
	v_and_b32_e32 v17, 0xffff0000, v17
	s_waitcnt vmcnt(0)
	v_lshlrev_b32_e32 v14, 16, v18
	v_pk_mul_f32 v[14:15], v[10:11], v[14:15]
	s_nop 0
	v_fma_f32 v15, v23, v25, v15
	v_add_f32_e32 v22, v14, v15
	v_and_b32_e32 v15, 0xffff0000, v2
	v_and_b32_e32 v14, 0xffff0000, v18
	v_pk_mul_f32 v[14:15], v[10:11], v[14:15]
	s_nop 0
	v_fma_f32 v2, v23, v26, v15
	v_add_f32_e32 v2, v14, v2
	v_lshlrev_b32_e32 v15, 16, v3
	v_lshlrev_b32_e32 v14, 16, v19
	v_pk_mul_f32 v[14:15], v[10:11], v[14:15]
	v_cvt_pk_bf16_f32 v2, v22, v2
	s_nop 0
	v_fma_f32 v15, v23, v27, v15
	v_add_f32_e32 v18, v14, v15
	v_and_b32_e32 v15, 0xffff0000, v3
	v_and_b32_e32 v14, 0xffff0000, v19
	v_pk_mul_f32 v[14:15], v[10:11], v[14:15]
	s_nop 0
	v_fma_f32 v3, v23, v28, v15
	v_add_f32_e32 v3, v14, v3
	v_lshlrev_b32_e32 v15, 16, v4
	v_lshlrev_b32_e32 v14, 16, v20
	v_pk_mul_f32 v[14:15], v[10:11], v[14:15]
	v_cvt_pk_bf16_f32 v3, v18, v3
	s_nop 0
	v_fma_f32 v15, v23, v29, v15
	v_add_f32_e32 v18, v14, v15
	v_and_b32_e32 v15, 0xffff0000, v4
	v_and_b32_e32 v14, 0xffff0000, v20
	v_pk_mul_f32 v[14:15], v[10:11], v[14:15]
	s_nop 0
	v_fma_f32 v4, v23, v16, v15
	v_add_f32_e32 v4, v14, v4
	v_lshlrev_b32_e32 v15, 16, v5
	v_lshlrev_b32_e32 v14, 16, v21
	v_pk_mul_f32 v[14:15], v[10:11], v[14:15]
	v_cvt_pk_bf16_f32 v4, v18, v4
	s_nop 0
	v_fma_f32 v15, v23, v30, v15
	v_add_f32_e32 v16, v14, v15
	v_and_b32_e32 v15, 0xffff0000, v5
	v_and_b32_e32 v14, 0xffff0000, v21
	v_pk_mul_f32 v[10:11], v[10:11], v[14:15]
	s_nop 0
	v_fma_f32 v5, v23, v17, v11
	v_add_f32_e32 v5, v10, v5
	v_mov_b64_e32 v[10:11], s[16:17]
	v_mad_i64_i32 v[10:11], s[4:5], v0, s12, v[10:11]
	s_mov_b32 s4, 0xbffff
	v_lshl_add_u64 v[8:9], v[8:9], 1, v[10:11]
	v_lshlrev_b32_e32 v0, 1, v24
	v_cmp_lt_i32_e32 vcc, s4, v6
	v_lshl_add_u64 v[8:9], v[8:9], 0, v[0:1]
	s_or_b64 s[2:3], vcc, s[2:3]
	v_cvt_pk_bf16_f32 v5, v16, v5
	global_store_dwordx4 v[8:9], v[2:5], off
	s_andn2_b64 exec, exec, s[2:3]
	s_cbranch_execnz .LBB0_785

; __device__ __forceinline__ unsigned pack2(float lo, float hi) { unsigned r; asm("v_cvt_pk_bf16_f32 %0, %1, %2" : "=v"(r) : "v"(lo), "v"(hi)); return r; }
; __device__ __forceinline__ float bflo(unsigned u) { return __uint_as_float(u << 16); }
; __device__ __forceinline__ float bfhi(unsigned u) { return __uint_as_float(u & 0xffff0000u); }
; __device__ void phase_mergeA(const Params& p, int l) {
;     ...
;   for (int i = blockIdx.x * NTHREADS + tid; i < totalB; i += gridDim.x * NTHREADS) {
;     const int c = i & 15, th = i >> 4, h = th & 3, tok = th >> 2;
;     const size_t off = (size_t)tok * 512 + h * 128 + c * 8;
;     const u32x4 a1 = *(const u32x4*)(p.oB + off), a2 = *(const u32x4*)(p.oB + (size_t)T_TOK * 512 + off);
;     float v[8]; float ss = 0.f;
; #pragma unroll
;     for (int e = 0; e < 4; ++e) {
;       v[2 * e] = bflo(a1[e]) - lam * bflo(a2[e]); v[2 * e + 1] = bfhi(a1[e]) - lam * bfhi(a2[e]);
;       ss += v[2 * e] * v[2 * e] + v[2 * e + 1] * v[2 * e + 1];
;     }
;     ss += __shfl_xor(ss, 1); ss += __shfl_xor(ss, 2); ss += __shfl_xor(ss, 4); ss += __shfl_xor(ss, 8);
;     const float sc = rsqrtf(ss * (1.f / 128.f) + 1e-6f) * sc0;
;     const f32x4 g0 = *(const f32x4*)(gs + c * 8), g1 = *(const f32x4*)(gs + c * 8 + 4);
;     u32x4 o;
;     o.x = pack2(v[0] * g0[0] * sc, v[1] * g0[1] * sc); o.y = pack2(v[2] * g0[2] * sc, v[3] * g0[3] * sc);
;     o.z = pack2(v[4] * g1[0] * sc, v[5] * g1[1] * sc); o.w = pack2(v[6] * g1[2] * sc, v[7] * g1[3] * sc);
;     *(u32x4*)(p.y + (size_t)tok * 1280 + 384 + h * 128 + c * 8) = o;
;   }
.LBB0_788:
	v_ashrrev_i32_e32 v10, 6, v12
	v_ashrrev_i32_e32 v11, 31, v10
	v_lshlrev_b64 v[2:3], 9, v[10:11]
	v_and_b32_e32 v0, 0x180, v13
	v_and_b32_e32 v32, 0x78, v13
	v_or3_b32 v2, v2, v0, v32
	v_lshlrev_b64 v[18:19], 1, v[2:3]
	v_lshl_add_u64 v[2:3], s[88:89], 0, v[18:19]
	v_lshl_add_u64 v[18:19], s[12:13], 0, v[18:19]
	global_load_dwordx4 v[2:5], v[2:3], off
	v_lshlrev_b32_e32 v8, 2, v32
	global_load_dwordx4 v[18:21], v[18:19], off
	global_load_dwordx4 v[52:55], v8, s[2:3] offset:16
	global_load_dwordx4 v[56:59], v8, s[2:3]
	v_lshlrev_b32_e32 v0, 1, v0
	v_add_u32_e32 v12, s72, v12
	v_add_u32_e32 v13, s14, v13
	s_waitcnt vmcnt(3)
	v_lshlrev_b32_e32 v23, 16, v3
	v_lshlrev_b32_e32 v22, 16, v2
	s_waitcnt vmcnt(2)
	v_lshlrev_b32_e32 v25, 16, v19
	v_lshlrev_b32_e32 v24, 16, v18
	v_and_b32_e32 v3, 0xffff0000, v3
	v_and_b32_e32 v2, 0xffff0000, v2
	v_and_b32_e32 v19, 0xffff0000, v19
	v_and_b32_e32 v18, 0xffff0000, v18
	v_pk_fma_f32 v[22:23], v[6:7], v[24:25], v[22:23] neg_lo:[1,0,0] neg_hi:[1,0,0]
	v_pk_fma_f32 v[24:25], v[6:7], v[18:19], v[2:3] neg_lo:[1,0,0] neg_hi:[1,0,0]
	v_lshlrev_b32_e32 v19, 16, v5
	v_lshlrev_b32_e32 v18, 16, v4
	v_lshlrev_b32_e32 v27, 16, v21
	v_lshlrev_b32_e32 v26, 16, v20
	v_pk_mul_f32 v[2:3], v[22:23], v[22:23]
	v_pk_fma_f32 v[26:27], v[6:7], v[26:27], v[18:19] neg_lo:[1,0,0] neg_hi:[1,0,0]
	v_and_b32_e32 v5, 0xffff0000, v5
	v_and_b32_e32 v4, 0xffff0000, v4
	v_and_b32_e32 v19, 0xffff0000, v21
	v_and_b32_e32 v18, 0xffff0000, v20
	v_pk_fma_f32 v[2:3], v[24:25], v[24:25], v[2:3]
	v_pk_fma_f32 v[28:29], v[6:7], v[18:19], v[4:5] neg_lo:[1,0,0] neg_hi:[1,0,0]
	v_pk_mul_f32 v[4:5], v[26:27], v[26:27]
	v_add_f32_e32 v2, v2, v3
	v_pk_fma_f32 v[4:5], v[28:29], v[28:29], v[4:5]
	s_nop 0
	v_add_f32_e32 v2, v4, v2
	v_add_f32_e32 v2, v5, v2
	ds_bpermute_b32 v3, v14, v2
	s_waitcnt lgkmcnt(0)
	v_add_f32_e32 v2, v2, v3
	ds_bpermute_b32 v3, v15, v2
	s_waitcnt lgkmcnt(0)
	v_add_f32_e32 v2, v2, v3
	ds_bpermute_b32 v3, v16, v2
	s_waitcnt lgkmcnt(0)
	v_add_f32_e32 v2, v2, v3
	ds_bpermute_b32 v3, v17, v2
	s_waitcnt lgkmcnt(0)
	v_add_f32_e32 v2, v2, v3
	v_fmamk_f32 v2, v2, 0x3c000000, v190
	v_cmp_gt_f32_e32 vcc, s15, v2
	v_mul_f32_e32 v3, 0x4b800000, v2
	s_nop 0
	v_cndmask_b32_e32 v2, v2, v3, vcc
	v_rsq_f32_e32 v2, v2
	s_nop 0
	v_mul_f32_e32 v3, 0x45800000, v2
	v_cndmask_b32_e32 v31, v2, v3, vcc
	s_waitcnt vmcnt(0)
	v_mov_b32_e32 v2, v52
	v_mov_b32_e32 v3, v53
	v_mov_b32_e32 v4, v54
	v_mov_b32_e32 v5, v55
	v_mov_b32_e32 v18, v56
	v_mov_b32_e32 v19, v57
	v_mov_b32_e32 v20, v58
	v_mov_b32_e32 v21, v59
	v_mov_b32_e32 v8, v27
	s_waitcnt vmcnt(1)
	v_mov_b32_e32 v30, v4
	s_waitcnt vmcnt(0)
	v_mul_f32_e32 v11, v22, v18
	v_mul_f32_e32 v22, v24, v19
	v_pk_mul_f32 v[18:19], v[8:9], v[30:31]
	v_mul_f32_e32 v20, v23, v20
	v_mul_f32_e32 v21, v25, v21
	v_mul_f32_e32 v23, v26, v2
	v_mul_f32_e32 v24, v28, v3
	v_mul_f32_e32 v2, v11, v19
	v_mul_f32_e32 v3, v22, v19
	v_cvt_pk_bf16_f32 v2, v2, v3
	v_mul_f32_e32 v3, v20, v19
	v_mul_f32_e32 v4, v21, v19
	v_cvt_pk_bf16_f32 v3, v3, v4
	v_mul_f32_e32 v4, v23, v19
	v_mul_f32_e32 v8, v24, v19
	v_mul_f32_e32 v5, v29, v5
	v_cvt_pk_bf16_f32 v4, v4, v8
	v_mul_f32_e32 v8, v18, v19
	v_mul_f32_e32 v5, v5, v19
	v_mov_b64_e32 v[18:19], s[56:57]
	v_mad_i64_i32 v[10:11], s[6:7], v10, s16, v[18:19]
	s_mov_b32 s6, 0xfffff
	v_lshl_add_u64 v[10:11], v[10:11], 0, v[0:1]
	v_lshlrev_b32_e32 v0, 1, v32
	v_cmp_lt_i32_e32 vcc, s6, v12
	v_lshl_add_u64 v[10:11], v[10:11], 0, v[0:1]
	s_or_b64 s[4:5], vcc, s[4:5]
	v_cvt_pk_bf16_f32 v5, v8, v5
	global_store_dwordx4 v[10:11], v[2:5], off offset:768
	s_andn2_b64 exec, exec, s[4:5]
	s_cbranch_execnz .LBB0_788

; __device__ void phase_experts_v(const Params& p, int l) {
;     ...
;     const float ss = wave_sum(x0 * x0 + x1 * x1);
;     if (lane == 0) p.ssqn[tok * 8 + x] = ss;
.LBB0_1236:
	v_pk_mul_f32 v[2:3], v[2:3], v[2:3]
	s_nop 0
	v_add_f32_e32 v2, v2, v3
	v_mov_b32_e32 v3, v2
	s_nop 1
	v_permlane32_swap_b32_e32 v2, v3
	v_add_f32_e32 v2, v2, v3
	v_mov_b32_e32 v3, v2
	s_nop 1
	v_permlane16_swap_b32_e32 v2, v3
	v_add_f32_e32 v2, v2, v3
	s_nop 1
	v_add_f32_dpp v2, v2, v2 row_ror:8 row_mask:0xf bank_mask:0xf
	s_nop 1
	v_add_f32_dpp v2, v2, v2 row_ror:4 row_mask:0xf bank_mask:0xf
	s_nop 1
	v_add_f32_dpp v2, v2, v2 row_ror:2 row_mask:0xf bank_mask:0xf
	s_nop 1
	v_add_f32_dpp v2, v2, v2 row_ror:1 row_mask:0xf bank_mask:0xf
	s_and_saveexec_b64 s[16:17], s[4:5]
	s_cbranch_execz .LBB0_1233
	v_readlane_b32 s56, v253, 61
	v_ashrrev_i32_e32 v11, 31, v10
	v_readlane_b32 s70, v254, 11
	v_readlane_b32 s71, v254, 12
	v_mov_b32_e32 v4, v2
	v_readlane_b32 s57, v253, 62
	v_lshl_add_u64 v[2:3], v[10:11], 2, s[70:71]
	v_readlane_b32 s58, v253, 63
	v_readlane_b32 s59, v254, 0
	v_readlane_b32 s60, v254, 1
	v_readlane_b32 s61, v254, 2
	v_readlane_b32 s62, v254, 3
	v_readlane_b32 s63, v254, 4
	v_readlane_b32 s64, v254, 5
	v_readlane_b32 s65, v254, 6
	v_readlane_b32 s66, v254, 7
	v_readlane_b32 s67, v254, 8
	v_readlane_b32 s68, v254, 9
	v_readlane_b32 s69, v254, 10
	global_store_dword v[2:3], v4, off
	s_branch .LBB0_1233
